# v10 + per-unit accumulator zeroing with v_mov_b64 (64 instead of 127 moves) in all six GEMM phases
# baseline (speedup 1.0000x reference)
.LBB0_171:
	v_mov_b64_e32 v[6:7], 0
	v_mov_b64_e32 v[8:9], 0
	v_mov_b64_e32 v[10:11], 0
	v_mov_b64_e32 v[12:13], 0
	v_mov_b64_e32 v[14:15], 0
	v_mov_b64_e32 v[16:17], 0
	v_mov_b64_e32 v[18:19], 0
	v_mov_b64_e32 v[20:21], 0
	v_mov_b64_e32 v[22:23], 0
	v_mov_b64_e32 v[24:25], 0
	v_mov_b64_e32 v[26:27], 0
	v_mov_b64_e32 v[28:29], 0
	v_mov_b64_e32 v[30:31], 0
	v_mov_b64_e32 v[32:33], 0
	v_mov_b64_e32 v[34:35], 0
	v_mov_b64_e32 v[36:37], 0
	v_mov_b64_e32 v[38:39], 0
	v_mov_b64_e32 v[40:41], 0
	v_mov_b64_e32 v[42:43], 0
	v_mov_b64_e32 v[44:45], 0
	v_mov_b64_e32 v[46:47], 0
	v_mov_b64_e32 v[48:49], 0
	v_mov_b64_e32 v[50:51], 0
	v_mov_b64_e32 v[52:53], 0
	v_mov_b64_e32 v[54:55], 0
	v_mov_b64_e32 v[56:57], 0
	v_mov_b64_e32 v[58:59], 0
	v_mov_b64_e32 v[60:61], 0
	v_mov_b64_e32 v[62:63], 0
	v_mov_b64_e32 v[64:65], 0
	v_mov_b64_e32 v[66:67], 0
	v_mov_b64_e32 v[68:69], 0
	v_mov_b64_e32 v[70:71], 0
	v_mov_b64_e32 v[72:73], 0
	v_mov_b64_e32 v[74:75], 0
	v_mov_b64_e32 v[76:77], 0
	v_mov_b64_e32 v[78:79], 0
	v_mov_b64_e32 v[80:81], 0
	v_mov_b64_e32 v[82:83], 0
	v_mov_b64_e32 v[84:85], 0
	v_mov_b64_e32 v[86:87], 0
	v_mov_b64_e32 v[88:89], 0
	v_mov_b64_e32 v[90:91], 0
	v_mov_b64_e32 v[92:93], 0
	v_mov_b64_e32 v[94:95], 0
	v_mov_b64_e32 v[96:97], 0
	v_mov_b64_e32 v[98:99], 0
	v_mov_b64_e32 v[100:101], 0
	v_mov_b64_e32 v[102:103], 0
	v_mov_b64_e32 v[104:105], 0
	v_mov_b64_e32 v[106:107], 0
	v_mov_b64_e32 v[108:109], 0
	v_mov_b64_e32 v[110:111], 0
	v_mov_b64_e32 v[112:113], 0
	v_mov_b64_e32 v[114:115], 0
	v_mov_b64_e32 v[116:117], 0
	v_mov_b64_e32 v[118:119], 0
	v_mov_b64_e32 v[120:121], 0
	v_mov_b64_e32 v[122:123], 0
	v_mov_b64_e32 v[124:125], 0
	v_mov_b64_e32 v[126:127], 0
	v_mov_b64_e32 v[128:129], 0
	v_mov_b64_e32 v[130:131], 0
	s_waitcnt lgkmcnt(0)
	v_mov_b32_e32 v5, v11
	v_mov_b32_e32 v4, v11
	s_mov_b32 s85, s24
	s_mov_b32 s92, s22

.LBB0_310:
	v_mov_b64_e32 v[6:7], 0
	v_mov_b64_e32 v[8:9], 0
	v_mov_b64_e32 v[10:11], 0
	v_mov_b64_e32 v[12:13], 0
	v_mov_b64_e32 v[14:15], 0
	v_mov_b64_e32 v[16:17], 0
	v_mov_b64_e32 v[18:19], 0
	v_mov_b64_e32 v[20:21], 0
	v_mov_b64_e32 v[22:23], 0
	v_mov_b64_e32 v[24:25], 0
	v_mov_b64_e32 v[26:27], 0
	v_mov_b64_e32 v[28:29], 0
	v_mov_b64_e32 v[30:31], 0
	v_mov_b64_e32 v[32:33], 0
	v_mov_b64_e32 v[34:35], 0
	v_mov_b64_e32 v[36:37], 0
	v_mov_b64_e32 v[38:39], 0
	v_mov_b64_e32 v[40:41], 0
	v_mov_b64_e32 v[42:43], 0
	v_mov_b64_e32 v[44:45], 0
	v_mov_b64_e32 v[46:47], 0
	v_mov_b64_e32 v[48:49], 0
	v_mov_b64_e32 v[50:51], 0
	v_mov_b64_e32 v[52:53], 0
	v_mov_b64_e32 v[54:55], 0
	v_mov_b64_e32 v[56:57], 0
	v_mov_b64_e32 v[58:59], 0
	v_mov_b64_e32 v[60:61], 0
	v_mov_b64_e32 v[62:63], 0
	v_mov_b64_e32 v[64:65], 0
	v_mov_b64_e32 v[66:67], 0
	v_mov_b64_e32 v[68:69], 0
	v_mov_b64_e32 v[70:71], 0
	v_mov_b64_e32 v[72:73], 0
	v_mov_b64_e32 v[74:75], 0
	v_mov_b64_e32 v[76:77], 0
	v_mov_b64_e32 v[78:79], 0
	v_mov_b64_e32 v[80:81], 0
	v_mov_b64_e32 v[82:83], 0
	v_mov_b64_e32 v[84:85], 0
	v_mov_b64_e32 v[86:87], 0
	v_mov_b64_e32 v[88:89], 0
	v_mov_b64_e32 v[90:91], 0
	v_mov_b64_e32 v[92:93], 0
	v_mov_b64_e32 v[94:95], 0
	v_mov_b64_e32 v[96:97], 0
	v_mov_b64_e32 v[98:99], 0
	v_mov_b64_e32 v[100:101], 0
	v_mov_b64_e32 v[102:103], 0
	v_mov_b64_e32 v[104:105], 0
	v_mov_b64_e32 v[106:107], 0
	v_mov_b64_e32 v[108:109], 0
	v_mov_b64_e32 v[110:111], 0
	v_mov_b64_e32 v[112:113], 0
	v_mov_b64_e32 v[114:115], 0
	v_mov_b64_e32 v[116:117], 0
	v_mov_b64_e32 v[118:119], 0
	v_mov_b64_e32 v[120:121], 0
	v_mov_b64_e32 v[122:123], 0
	v_mov_b64_e32 v[124:125], 0
	v_mov_b64_e32 v[126:127], 0
	v_mov_b64_e32 v[128:129], 0
	v_mov_b64_e32 v[130:131], 0
	s_waitcnt lgkmcnt(0)
	v_mov_b32_e32 v5, v11
	v_mov_b32_e32 v4, v11
	s_mov_b32 s74, s26
	s_mov_b32 s75, s24

.LBB0_794:
	v_mov_b64_e32 v[6:7], 0
	v_mov_b64_e32 v[8:9], 0
	v_mov_b64_e32 v[10:11], 0
	v_mov_b64_e32 v[12:13], 0
	v_mov_b64_e32 v[14:15], 0
	v_mov_b64_e32 v[16:17], 0
	v_mov_b64_e32 v[18:19], 0
	v_mov_b64_e32 v[20:21], 0
	v_mov_b64_e32 v[22:23], 0
	v_mov_b64_e32 v[24:25], 0
	v_mov_b64_e32 v[26:27], 0
	v_mov_b64_e32 v[28:29], 0
	v_mov_b64_e32 v[30:31], 0
	v_mov_b64_e32 v[32:33], 0
	v_mov_b64_e32 v[34:35], 0
	v_mov_b64_e32 v[36:37], 0
	v_mov_b64_e32 v[38:39], 0
	v_mov_b64_e32 v[40:41], 0
	v_mov_b64_e32 v[42:43], 0
	v_mov_b64_e32 v[44:45], 0
	v_mov_b64_e32 v[46:47], 0
	v_mov_b64_e32 v[48:49], 0
	v_mov_b64_e32 v[50:51], 0
	v_mov_b64_e32 v[52:53], 0
	v_mov_b64_e32 v[54:55], 0
	v_mov_b64_e32 v[56:57], 0
	v_mov_b64_e32 v[58:59], 0
	v_mov_b64_e32 v[60:61], 0
	v_mov_b64_e32 v[62:63], 0
	v_mov_b64_e32 v[64:65], 0
	v_mov_b64_e32 v[66:67], 0
	v_mov_b64_e32 v[68:69], 0
	v_mov_b64_e32 v[70:71], 0
	v_mov_b64_e32 v[72:73], 0
	v_mov_b64_e32 v[74:75], 0
	v_mov_b64_e32 v[76:77], 0
	v_mov_b64_e32 v[78:79], 0
	v_mov_b64_e32 v[80:81], 0
	v_mov_b64_e32 v[82:83], 0
	v_mov_b64_e32 v[84:85], 0
	v_mov_b64_e32 v[86:87], 0
	v_mov_b64_e32 v[88:89], 0
	v_mov_b64_e32 v[90:91], 0
	v_mov_b64_e32 v[92:93], 0
	v_mov_b64_e32 v[94:95], 0
	v_mov_b64_e32 v[96:97], 0
	v_mov_b64_e32 v[98:99], 0
	v_mov_b64_e32 v[100:101], 0
	v_mov_b64_e32 v[102:103], 0
	v_mov_b64_e32 v[104:105], 0
	v_mov_b64_e32 v[106:107], 0
	v_mov_b64_e32 v[108:109], 0
	v_mov_b64_e32 v[110:111], 0
	v_mov_b64_e32 v[112:113], 0
	v_mov_b64_e32 v[114:115], 0
	v_mov_b64_e32 v[116:117], 0
	v_mov_b64_e32 v[118:119], 0
	v_mov_b64_e32 v[120:121], 0
	v_mov_b64_e32 v[122:123], 0
	v_mov_b64_e32 v[124:125], 0
	v_mov_b64_e32 v[126:127], 0
	v_mov_b64_e32 v[128:129], 0
	v_mov_b64_e32 v[130:131], 0
	s_waitcnt lgkmcnt(0)
	v_mov_b32_e32 v5, v11
	v_mov_b32_e32 v4, v11
	s_mov_b32 s3, s26
	s_mov_b32 s54, s24

.LBB0_974:
	s_ashr_i32 s25, s24, 31
	s_lshl_b64 s[26:27], s[24:25], 20
	s_add_u32 s26, s1, s26
	s_addc_u32 s27, s3, s27
	s_and_b64 s[28:29], s[8:9], exec
	s_cselect_b32 s25, s27, s31
	s_cselect_b32 s66, s26, s30
	s_ashr_i32 s23, s22, 31
	s_lshl_b64 s[28:29], s[22:23], 20
	s_add_u32 s28, s10, s28
	s_addc_u32 s29, s11, s29
	s_and_b64 s[36:37], s[8:9], exec
	s_cselect_b32 s23, s29, s35
	s_cselect_b32 s67, s28, s34
	s_add_u32 s30, s30, 0x80080
	s_addc_u32 s31, s31, 0
	s_add_u32 s69, s34, 0x100
	s_addc_u32 s74, s35, 0
	s_mov_b32 s75, -2
	s_waitcnt lgkmcnt(0)
	v_mov_b64_e32 v[4:5], 0
	v_mov_b64_e32 v[6:7], 0
	v_mov_b64_e32 v[8:9], 0
	v_mov_b64_e32 v[10:11], 0
	v_mov_b64_e32 v[12:13], 0
	v_mov_b64_e32 v[14:15], 0
	v_mov_b64_e32 v[16:17], 0
	v_mov_b64_e32 v[18:19], 0
	v_mov_b64_e32 v[20:21], 0
	v_mov_b64_e32 v[22:23], 0
	v_mov_b64_e32 v[24:25], 0
	v_mov_b64_e32 v[26:27], 0
	v_mov_b64_e32 v[28:29], 0
	v_mov_b64_e32 v[30:31], 0
	v_mov_b64_e32 v[32:33], 0
	v_mov_b64_e32 v[34:35], 0
	v_mov_b64_e32 v[36:37], 0
	v_mov_b64_e32 v[38:39], 0
	v_mov_b64_e32 v[40:41], 0
	v_mov_b64_e32 v[42:43], 0
	v_mov_b64_e32 v[44:45], 0
	v_mov_b64_e32 v[46:47], 0
	v_mov_b64_e32 v[48:49], 0
	v_mov_b64_e32 v[50:51], 0
	v_mov_b64_e32 v[52:53], 0
	v_mov_b64_e32 v[54:55], 0
	v_mov_b64_e32 v[56:57], 0
	v_mov_b64_e32 v[58:59], 0
	v_mov_b64_e32 v[60:61], 0
	v_mov_b64_e32 v[62:63], 0
	v_mov_b64_e32 v[64:65], 0
	v_mov_b64_e32 v[66:67], 0
	v_mov_b64_e32 v[68:69], 0
	v_mov_b64_e32 v[70:71], 0
	v_mov_b64_e32 v[72:73], 0
	v_mov_b64_e32 v[74:75], 0
	v_mov_b64_e32 v[76:77], 0
	v_mov_b64_e32 v[78:79], 0
	v_mov_b64_e32 v[80:81], 0
	v_mov_b64_e32 v[82:83], 0
	v_mov_b64_e32 v[84:85], 0
	v_mov_b64_e32 v[86:87], 0
	v_mov_b64_e32 v[88:89], 0
	v_mov_b64_e32 v[90:91], 0
	v_mov_b64_e32 v[92:93], 0
	v_mov_b64_e32 v[94:95], 0
	v_mov_b64_e32 v[96:97], 0
	v_mov_b64_e32 v[98:99], 0
	v_mov_b64_e32 v[100:101], 0
	v_mov_b64_e32 v[102:103], 0
	v_mov_b64_e32 v[104:105], 0
	v_mov_b64_e32 v[106:107], 0
	v_mov_b64_e32 v[108:109], 0
	v_mov_b64_e32 v[110:111], 0
	v_mov_b64_e32 v[112:113], 0
	v_mov_b64_e32 v[114:115], 0
	v_mov_b64_e32 v[116:117], 0
	v_mov_b64_e32 v[118:119], 0
	v_mov_b64_e32 v[120:121], 0
	v_mov_b64_e32 v[122:123], 0
	v_mov_b64_e32 v[124:125], 0
	v_mov_b64_e32 v[126:127], 0
	v_mov_b64_e32 v[128:129], 0
	v_mov_b64_e32 v[130:131], 0

.LBB0_1062:
	v_mov_b64_e32 v[6:7], 0
	v_mov_b64_e32 v[8:9], 0
	v_mov_b64_e32 v[10:11], 0
	v_mov_b64_e32 v[12:13], 0
	v_mov_b64_e32 v[14:15], 0
	v_mov_b64_e32 v[16:17], 0
	v_mov_b64_e32 v[18:19], 0
	v_mov_b64_e32 v[20:21], 0
	v_mov_b64_e32 v[22:23], 0
	v_mov_b64_e32 v[24:25], 0
	v_mov_b64_e32 v[26:27], 0
	v_mov_b64_e32 v[28:29], 0
	v_mov_b64_e32 v[30:31], 0
	v_mov_b64_e32 v[32:33], 0
	v_mov_b64_e32 v[34:35], 0
	v_mov_b64_e32 v[36:37], 0
	v_mov_b64_e32 v[38:39], 0
	v_mov_b64_e32 v[40:41], 0
	v_mov_b64_e32 v[42:43], 0
	v_mov_b64_e32 v[44:45], 0
	v_mov_b64_e32 v[46:47], 0
	v_mov_b64_e32 v[48:49], 0
	v_mov_b64_e32 v[50:51], 0
	v_mov_b64_e32 v[52:53], 0
	v_mov_b64_e32 v[54:55], 0
	v_mov_b64_e32 v[56:57], 0
	v_mov_b64_e32 v[58:59], 0
	v_mov_b64_e32 v[60:61], 0
	v_mov_b64_e32 v[62:63], 0
	v_mov_b64_e32 v[64:65], 0
	v_mov_b64_e32 v[66:67], 0
	v_mov_b64_e32 v[68:69], 0
	v_mov_b64_e32 v[70:71], 0
	v_mov_b64_e32 v[72:73], 0
	v_mov_b64_e32 v[74:75], 0
	v_mov_b64_e32 v[76:77], 0
	v_mov_b64_e32 v[78:79], 0
	v_mov_b64_e32 v[80:81], 0
	v_mov_b64_e32 v[82:83], 0
	v_mov_b64_e32 v[84:85], 0
	v_mov_b64_e32 v[86:87], 0
	v_mov_b64_e32 v[88:89], 0
	v_mov_b64_e32 v[90:91], 0
	v_mov_b64_e32 v[92:93], 0
	v_mov_b64_e32 v[94:95], 0
	v_mov_b64_e32 v[96:97], 0
	v_mov_b64_e32 v[98:99], 0
	v_mov_b64_e32 v[100:101], 0
	v_mov_b64_e32 v[102:103], 0
	v_mov_b64_e32 v[104:105], 0
	v_mov_b64_e32 v[106:107], 0
	v_mov_b64_e32 v[108:109], 0
	v_mov_b64_e32 v[110:111], 0
	v_mov_b64_e32 v[112:113], 0
	v_mov_b64_e32 v[114:115], 0
	v_mov_b64_e32 v[116:117], 0
	v_mov_b64_e32 v[118:119], 0
	v_mov_b64_e32 v[120:121], 0
	v_mov_b64_e32 v[122:123], 0
	v_mov_b64_e32 v[124:125], 0
	v_mov_b64_e32 v[126:127], 0
	v_mov_b64_e32 v[128:129], 0
	v_mov_b64_e32 v[130:131], 0
	s_waitcnt lgkmcnt(0)
	v_mov_b32_e32 v5, v11
	v_mov_b32_e32 v4, v11
	s_mov_b32 s66, s24
	s_mov_b32 s67, s22

.LBB0_1204:
	s_add_u32 s52, s24, 0x100
	s_addc_u32 s54, s25, 0
	s_mov_b32 s66, -2
	s_waitcnt lgkmcnt(0)
	v_mov_b64_e32 v[4:5], 0
	v_mov_b64_e32 v[6:7], 0
	v_mov_b64_e32 v[8:9], 0
	v_mov_b64_e32 v[10:11], 0
	v_mov_b64_e32 v[12:13], 0
	v_mov_b64_e32 v[14:15], 0
	v_mov_b64_e32 v[16:17], 0
	v_mov_b64_e32 v[18:19], 0
	v_mov_b64_e32 v[20:21], 0
	v_mov_b64_e32 v[22:23], 0
	v_mov_b64_e32 v[24:25], 0
	v_mov_b64_e32 v[26:27], 0
	v_mov_b64_e32 v[28:29], 0
	v_mov_b64_e32 v[30:31], 0
	v_mov_b64_e32 v[32:33], 0
	v_mov_b64_e32 v[34:35], 0
	v_mov_b64_e32 v[36:37], 0
	v_mov_b64_e32 v[38:39], 0
	v_mov_b64_e32 v[40:41], 0
	v_mov_b64_e32 v[42:43], 0
	v_mov_b64_e32 v[44:45], 0
	v_mov_b64_e32 v[46:47], 0
	v_mov_b64_e32 v[48:49], 0
	v_mov_b64_e32 v[50:51], 0
	v_mov_b64_e32 v[52:53], 0
	v_mov_b64_e32 v[54:55], 0
	v_mov_b64_e32 v[56:57], 0
	v_mov_b64_e32 v[58:59], 0
	v_mov_b64_e32 v[60:61], 0
	v_mov_b64_e32 v[62:63], 0
	v_mov_b64_e32 v[64:65], 0
	v_mov_b64_e32 v[66:67], 0
	v_mov_b64_e32 v[68:69], 0
	v_mov_b64_e32 v[70:71], 0
	v_mov_b64_e32 v[72:73], 0
	v_mov_b64_e32 v[74:75], 0
	v_mov_b64_e32 v[76:77], 0
	v_mov_b64_e32 v[78:79], 0
	v_mov_b64_e32 v[80:81], 0
	v_mov_b64_e32 v[82:83], 0
	v_mov_b64_e32 v[84:85], 0
	v_mov_b64_e32 v[86:87], 0
	v_mov_b64_e32 v[88:89], 0
	v_mov_b64_e32 v[90:91], 0
	v_mov_b64_e32 v[92:93], 0
	v_mov_b64_e32 v[94:95], 0
	v_mov_b64_e32 v[96:97], 0
	v_mov_b64_e32 v[98:99], 0
	v_mov_b64_e32 v[100:101], 0
	v_mov_b64_e32 v[102:103], 0
	v_mov_b64_e32 v[104:105], 0
	v_mov_b64_e32 v[106:107], 0
	v_mov_b64_e32 v[108:109], 0
	v_mov_b64_e32 v[110:111], 0
	v_mov_b64_e32 v[112:113], 0
	v_mov_b64_e32 v[114:115], 0
	v_mov_b64_e32 v[116:117], 0
	v_mov_b64_e32 v[118:119], 0
	v_mov_b64_e32 v[120:121], 0
	v_mov_b64_e32 v[122:123], 0
	v_mov_b64_e32 v[124:125], 0
	v_mov_b64_e32 v[126:127], 0
	v_mov_b64_e32 v[128:129], 0
	v_mov_b64_e32 v[130:131], 0
